# K-loop: extra priority dip (s_setprio 0/1) after every 8 MFMAs so the loading half gets issue slots more often
# speedup vs baseline: 1.0020x; 1.0020x over previous
; #define PG8_LDA(dst, b, h) do { _Pragma("unroll") for (int m = 0; m < 4; ++m) _Pragma("unroll") for (int k = 0; k < 2; ++k) dst[m][k] = *(const LAS bf16x8*)(lds + PG8_SA(b, h) + aoff + m * 2048 + k * 1024); } while (0)
; #define PG8_LDB(dst, b, h) do { _Pragma("unroll") for (int n = 0; n < 2; ++n) _Pragma("unroll") for (int k = 0; k < 2; ++k) dst[n][k] = *(const LAS bf16x8*)(lds + PG8_SB(b, h) + boff + n * 2048 + k * 1024); } while (0)
; #define PG8_MMA(ai, bj, At, Bt) do { __builtin_amdgcn_s_setprio(1); _Pragma("unroll") for (int m = 0; m < 4; ++m) _Pragma("unroll") for (int n = 0; n < 2; ++n) _Pragma("unroll") for (int k = 0; k < 2; ++k) \
;         acc[ai][bj][m][n] = __builtin_amdgcn_mfma_f32_16x16x32_bf16(Bt[n][k], At[m][k], acc[ai][bj][m][n], 0, 0, 0); __builtin_amdgcn_s_setprio(0); } while (0)
; #define PG8_WAIT_V(n) asm volatile("s_waitcnt vmcnt(" #n ")" ::: "memory")
; #define PG8_WAIT_L(n) asm volatile("s_waitcnt lgkmcnt(" #n ")" ::: "memory")
; #define PG8_BAR __builtin_amdgcn_s_barrier()
; #define PG8_SCHED __builtin_amdgcn_sched_barrier(0)
; #define PG8_STA(bufoff, gbase, ld) PG8_STAGE(bufoff, gbase, RA0 * (unsigned)(ld) + CC0, RA1 * (unsigned)(ld) + CC1)
; #define PG8_STB(bufoff, gbase, ld) PG8_STAGE(bufoff, gbase, RB0 * (unsigned)(ld) + CC0, RB1 * (unsigned)(ld) + CC1)
; __device__ __forceinline__ void gemm_phase(LAS unsigned char* lds, const Sched& S, const Epi& E) {
;     ...
;             PG8_LDB(B0, 0, 0); PG8_LDB(B1, 0, 1); PG8_SCHED; PG8_LDA(At, 0, 0); PG8_STA(PG8_SA(1, 1), a1 + hA, lda);
;             PG8_WAIT_V(8); PG8_WAIT_L(0); PG8_BAR; PG8_MMA(0, 0, At, B0); PG8_MMA(0, 1, At, B1); PG8_BAR; PG8_SCHED;
;             PG8_LDA(At, 0, 1); PG8_STB(PG8_SB(0, 0), b2, xldb); PG8_STB(PG8_SB(0, 1), b2 + xhB, xldb); PG8_STA(PG8_SA(0, 0), a2, xlda);
;             PG8_WAIT_V(8); PG8_WAIT_L(0); PG8_BAR; PG8_MMA(1, 0, At, B0); PG8_MMA(1, 1, At, B1); PG8_BAR; PG8_SCHED;
.LBB0_263:
	s_add_i32 s24, s8, 2
	s_add_u32 s26, vcc_lo, 0x80
	s_addc_u32 s9, vcc_hi, 0
	s_add_i32 s37, 0, 0x10000
	s_cmp_eq_u32 s21, s8
	s_cselect_b32 s9, s7, s9
	s_cselect_b32 s8, s6, s26
	s_cselect_b32 s92, s11, s61
	s_cselect_b32 s30, s22, s20
	v_add_u32_e32 v0, s37, v241
	s_cselect_b32 s29, s13, s72
	s_cselect_b32 s28, s12, s2
	s_add_i32 s57, 0, 0x14000
	ds_read_b128 v[134:137], v0
	ds_read_b128 v[138:141], v0 offset:1024
	ds_read_b128 v[142:145], v0 offset:2048
	ds_read_b128 v[146:149], v0 offset:3072
	v_add_u32_e32 v0, s57, v241
	ds_read_b128 v[150:153], v0
	ds_read_b128 v[154:157], v0 offset:1024
	ds_read_b128 v[158:161], v0 offset:2048
	ds_read_b128 v[162:165], v0 offset:3072
	s_mov_b32 s93, s31
	s_lshl_b64 s[26:27], s[30:31], 8
	v_add_u32_e32 v0, 0, v240
	v_lshl_add_u64 v[214:215], vcc, 0, v[130:131]
	s_add_i32 m0, s34, 0xc000
	ds_read_b128 v[166:169], v0
	ds_read_b128 v[170:173], v0 offset:1024
	ds_read_b128 v[174:177], v0 offset:2048
	ds_read_b128 v[178:181], v0 offset:3072
	ds_read_b128 v[182:185], v0 offset:4096
	ds_read_b128 v[186:189], v0 offset:5120
	ds_read_b128 v[190:193], v0 offset:6144
	ds_read_b128 v[210:213], v0 offset:7168
	global_load_lds_dwordx4 v[214:215], off
	v_lshl_add_u64 v[214:215], vcc, 0, v[132:133]
	s_add_i32 m0, s34, 0xe000
	s_nop 0
	global_load_lds_dwordx4 v[214:215], off
	s_waitcnt vmcnt(8)
	s_waitcnt lgkmcnt(0)
	s_barrier
	s_setprio 1
	s_waitcnt lgkmcnt(0)
	v_mfma_f32_16x16x32_bf16 v[126:129], v[134:137], v[166:169], v[126:129]
	v_mfma_f32_16x16x32_bf16 v[122:125], v[142:145], v[166:169], v[122:125]
	v_mfma_f32_16x16x32_bf16 v[110:113], v[134:137], v[174:177], v[110:113]
	v_mfma_f32_16x16x32_bf16 v[106:109], v[142:145], v[174:177], v[106:109]
	v_mfma_f32_16x16x32_bf16 v[98:101], v[134:137], v[182:185], v[98:101]
	v_mfma_f32_16x16x32_bf16 v[90:93], v[142:145], v[182:185], v[90:93]
	v_mfma_f32_16x16x32_bf16 v[82:85], v[134:137], v[190:193], v[82:85]
	v_mfma_f32_16x16x32_bf16 v[74:77], v[142:145], v[190:193], v[74:77]
	s_setprio 0
	s_setprio 1
	v_mfma_f32_16x16x32_bf16 v[126:129], v[138:141], v[170:173], v[126:129]
	v_mfma_f32_16x16x32_bf16 v[122:125], v[146:149], v[170:173], v[122:125]
	v_mfma_f32_16x16x32_bf16 v[110:113], v[138:141], v[178:181], v[110:113]
	v_mfma_f32_16x16x32_bf16 v[106:109], v[146:149], v[178:181], v[106:109]
	v_mfma_f32_16x16x32_bf16 v[98:101], v[138:141], v[186:189], v[98:101]
	v_mfma_f32_16x16x32_bf16 v[90:93], v[146:149], v[186:189], v[90:93]
	v_mfma_f32_16x16x32_bf16 v[82:85], v[138:141], v[210:213], v[82:85]
	v_mfma_f32_16x16x32_bf16 v[74:77], v[146:149], v[210:213], v[74:77]
	s_setprio 0
	s_setprio 1
	v_mfma_f32_16x16x32_bf16 v[118:121], v[150:153], v[166:169], v[118:121]
	v_mfma_f32_16x16x32_bf16 v[114:117], v[158:161], v[166:169], v[114:117]
	v_mfma_f32_16x16x32_bf16 v[102:105], v[150:153], v[174:177], v[102:105]
	v_mfma_f32_16x16x32_bf16 v[94:97], v[158:161], v[174:177], v[94:97]
	v_mfma_f32_16x16x32_bf16 v[86:89], v[150:153], v[182:185], v[86:89]
	v_mfma_f32_16x16x32_bf16 v[78:81], v[158:161], v[182:185], v[78:81]
	v_mfma_f32_16x16x32_bf16 v[70:73], v[150:153], v[190:193], v[70:73]
	v_mfma_f32_16x16x32_bf16 v[66:69], v[158:161], v[190:193], v[66:69]
	s_setprio 0
	s_setprio 1
	v_mfma_f32_16x16x32_bf16 v[118:121], v[154:157], v[170:173], v[118:121]
	v_mfma_f32_16x16x32_bf16 v[114:117], v[162:165], v[170:173], v[114:117]
	v_mfma_f32_16x16x32_bf16 v[102:105], v[154:157], v[178:181], v[102:105]
	v_mfma_f32_16x16x32_bf16 v[94:97], v[162:165], v[178:181], v[94:97]
	v_mfma_f32_16x16x32_bf16 v[86:89], v[154:157], v[186:189], v[86:89]
	v_mfma_f32_16x16x32_bf16 v[78:81], v[162:165], v[186:189], v[78:81]
	v_mfma_f32_16x16x32_bf16 v[70:73], v[154:157], v[210:213], v[70:73]
	v_mfma_f32_16x16x32_bf16 v[66:69], v[162:165], v[210:213], v[66:69]
	s_setprio 0
	s_barrier
	s_add_i32 s37, s37, s25
	v_mad_u64_u32 v[214:215], s[80:81], s92, v237, v[194:195]
	s_mov_b32 m0, s37
	ds_read_b128 v[166:169], v0 offset:16384
	ds_read_b128 v[170:173], v0 offset:17408
	ds_read_b128 v[174:177], v0 offset:18432
	ds_read_b128 v[178:181], v0 offset:19456
	ds_read_b128 v[182:185], v0 offset:20480
	ds_read_b128 v[186:189], v0 offset:21504
	ds_read_b128 v[190:193], v0 offset:22528
	ds_read_b128 v[210:213], v0 offset:23552
	s_lshl_b64 s[74:75], s[92:93], 8
	global_load_lds_dwordx4 v214, s[28:29]
	s_add_i32 m0, s37, 0x2000
	s_add_u32 s74, s28, s74
	v_mad_u64_u32 v[216:217], s[80:81], s92, v238, v[196:197]
	s_addc_u32 s75, s29, s75
	s_add_i32 s37, s57, s25
	global_load_lds_dwordx4 v216, s[28:29]
	s_mov_b32 m0, s37
	v_mad_u64_u32 v[218:219], s[80:81], s30, v235, v[194:195]
	global_load_lds_dwordx4 v214, s[74:75]
	s_add_i32 m0, s37, 0x2000
	v_mad_u64_u32 v[220:221], s[80:81], s30, v236, v[196:197]
	global_load_lds_dwordx4 v216, s[74:75]
	s_mov_b32 m0, s34
	v_mov_b32_e32 v215, v1
	global_load_lds_dwordx4 v218, s[8:9]
	s_mov_b32 m0, s35
	v_mov_b32_e32 v217, v1
	global_load_lds_dwordx4 v220, s[8:9]
	v_mov_b32_e32 v219, v1
	v_mov_b32_e32 v221, v1
	v_lshl_add_u64 v[222:223], s[28:29], 0, v[214:215]
	v_lshl_add_u64 v[224:225], s[28:29], 0, v[216:217]
	v_lshl_add_u64 v[214:215], s[74:75], 0, v[214:215]
	v_lshl_add_u64 v[216:217], s[74:75], 0, v[216:217]
	v_lshl_add_u64 v[226:227], s[8:9], 0, v[218:219]
	v_lshl_add_u64 v[228:229], s[8:9], 0, v[220:221]
	s_waitcnt vmcnt(8)
	s_waitcnt lgkmcnt(0)
	s_barrier
; #define PG8_LDA(dst, b, h) do { _Pragma("unroll") for (int m = 0; m < 4; ++m) _Pragma("unroll") for (int k = 0; k < 2; ++k) dst[m][k] = *(const LAS bf16x8*)(lds + PG8_SA(b, h) + aoff + m * 2048 + k * 1024); } while (0)
; #define PG8_LDB(dst, b, h) do { _Pragma("unroll") for (int n = 0; n < 2; ++n) _Pragma("unroll") for (int k = 0; k < 2; ++k) dst[n][k] = *(const LAS bf16x8*)(lds + PG8_SB(b, h) + boff + n * 2048 + k * 1024); } while (0)
; #define PG8_MMA(ai, bj, At, Bt) do { __builtin_amdgcn_s_setprio(1); _Pragma("unroll") for (int m = 0; m < 4; ++m) _Pragma("unroll") for (int n = 0; n < 2; ++n) _Pragma("unroll") for (int k = 0; k < 2; ++k) \
;         acc[ai][bj][m][n] = __builtin_amdgcn_mfma_f32_16x16x32_bf16(Bt[n][k], At[m][k], acc[ai][bj][m][n], 0, 0, 0); __builtin_amdgcn_s_setprio(0); } while (0)
; #define PG8_WAIT_V(n) asm volatile("s_waitcnt vmcnt(" #n ")" ::: "memory")
; #define PG8_WAIT_L(n) asm volatile("s_waitcnt lgkmcnt(" #n ")" ::: "memory")
; #define PG8_BAR __builtin_amdgcn_s_barrier()
; #define PG8_SCHED __builtin_amdgcn_sched_barrier(0)
; #define PG8_STA(bufoff, gbase, ld) PG8_STAGE(bufoff, gbase, RA0 * (unsigned)(ld) + CC0, RA1 * (unsigned)(ld) + CC1)
; __device__ __forceinline__ void gemm_phase(LAS unsigned char* lds, const Sched& S, const Epi& E) {
;     ...
;             PG8_WAIT_V(8); PG8_WAIT_L(0); PG8_BAR; PG8_MMA(1, 0, At, B0); PG8_MMA(1, 1, At, B1); PG8_BAR; PG8_SCHED;
;             PG8_LDB(B0, 1, 0); PG8_LDB(B1, 1, 1); PG8_SCHED; PG8_LDA(At, 1, 0); PG8_STA(PG8_SA(0, 1), a2 + xhA, xlda);
;             PG8_WAIT_V(8); PG8_WAIT_L(0); PG8_BAR; PG8_MMA(0, 0, At, B0); PG8_MMA(0, 1, At, B1); PG8_BAR; PG8_SCHED;
	s_setprio 1
	s_waitcnt lgkmcnt(0)
	v_mfma_f32_16x16x32_bf16 v[62:65], v[134:137], v[166:169], v[62:65]
	v_mfma_f32_16x16x32_bf16 v[58:61], v[142:145], v[166:169], v[58:61]
	v_mfma_f32_16x16x32_bf16 v[46:49], v[134:137], v[174:177], v[46:49]
	v_mfma_f32_16x16x32_bf16 v[42:45], v[142:145], v[174:177], v[42:45]
	v_mfma_f32_16x16x32_bf16 v[30:33], v[134:137], v[182:185], v[30:33]
	v_mfma_f32_16x16x32_bf16 v[26:29], v[142:145], v[182:185], v[26:29]
	v_mfma_f32_16x16x32_bf16 v[14:17], v[134:137], v[190:193], v[14:17]
	v_mfma_f32_16x16x32_bf16 v[10:13], v[142:145], v[190:193], v[10:13]
	s_setprio 0
	s_setprio 1
	v_mfma_f32_16x16x32_bf16 v[62:65], v[138:141], v[170:173], v[62:65]
	v_mfma_f32_16x16x32_bf16 v[58:61], v[146:149], v[170:173], v[58:61]
	v_mfma_f32_16x16x32_bf16 v[46:49], v[138:141], v[178:181], v[46:49]
	v_mfma_f32_16x16x32_bf16 v[42:45], v[146:149], v[178:181], v[42:45]
	v_mfma_f32_16x16x32_bf16 v[30:33], v[138:141], v[186:189], v[30:33]
	v_mfma_f32_16x16x32_bf16 v[26:29], v[146:149], v[186:189], v[26:29]
	v_mfma_f32_16x16x32_bf16 v[14:17], v[138:141], v[210:213], v[14:17]
	v_mfma_f32_16x16x32_bf16 v[10:13], v[146:149], v[210:213], v[10:13]
	s_setprio 0
	s_setprio 1
	v_mfma_f32_16x16x32_bf16 v[54:57], v[150:153], v[166:169], v[54:57]
	v_mfma_f32_16x16x32_bf16 v[50:53], v[158:161], v[166:169], v[50:53]
	v_mfma_f32_16x16x32_bf16 v[38:41], v[150:153], v[174:177], v[38:41]
	v_mfma_f32_16x16x32_bf16 v[34:37], v[158:161], v[174:177], v[34:37]
	v_mfma_f32_16x16x32_bf16 v[22:25], v[150:153], v[182:185], v[22:25]
	v_mfma_f32_16x16x32_bf16 v[18:21], v[158:161], v[182:185], v[18:21]
	v_mfma_f32_16x16x32_bf16 v[6:9], v[150:153], v[190:193], v[6:9]
	v_mfma_f32_16x16x32_bf16 v[2:5], v[158:161], v[190:193], v[2:5]
	s_setprio 0
	s_setprio 1
	v_mfma_f32_16x16x32_bf16 v[54:57], v[154:157], v[170:173], v[54:57]
	v_mfma_f32_16x16x32_bf16 v[50:53], v[162:165], v[170:173], v[50:53]
	v_mfma_f32_16x16x32_bf16 v[38:41], v[154:157], v[178:181], v[38:41]
	v_mfma_f32_16x16x32_bf16 v[34:37], v[162:165], v[178:181], v[34:37]
	v_mfma_f32_16x16x32_bf16 v[22:25], v[154:157], v[186:189], v[22:25]
	v_mfma_f32_16x16x32_bf16 v[18:21], v[162:165], v[186:189], v[18:21]
	v_mfma_f32_16x16x32_bf16 v[6:9], v[154:157], v[210:213], v[6:9]
	v_mfma_f32_16x16x32_bf16 v[2:5], v[162:165], v[210:213], v[2:5]
	s_setprio 0
	s_barrier
	s_add_i32 s28, 0, 0x18000
	s_add_i32 s29, 0, 0x1c000
	v_add_u32_e32 v146, s28, v241
	v_add_u32_e32 v162, s29, v241
	ds_read_b128 v[134:137], v146
	ds_read_b128 v[138:141], v146 offset:1024
	ds_read_b128 v[142:145], v146 offset:2048
	ds_read_b128 v[146:149], v146 offset:3072
	ds_read_b128 v[150:153], v162
	ds_read_b128 v[154:157], v162 offset:1024
	ds_read_b128 v[158:161], v162 offset:2048
	ds_read_b128 v[162:165], v162 offset:3072
	s_add_u32 s8, s8, s26
	s_addc_u32 s9, s9, s27
	s_mov_b32 m0, s39
	ds_read_b128 v[166:169], v0 offset:32768
	ds_read_b128 v[170:173], v0 offset:33792
	ds_read_b128 v[174:177], v0 offset:34816
	ds_read_b128 v[178:181], v0 offset:35840
	ds_read_b128 v[182:185], v0 offset:36864
	ds_read_b128 v[186:189], v0 offset:37888
	ds_read_b128 v[190:193], v0 offset:38912
	ds_read_b128 v[210:213], v0 offset:39936
	global_load_lds_dwordx4 v218, s[8:9]
	s_mov_b32 m0, s91
	s_nop 0
	global_load_lds_dwordx4 v220, s[8:9]
	s_waitcnt vmcnt(8)
	s_waitcnt lgkmcnt(0)
	s_barrier
	s_setprio 1
	s_waitcnt lgkmcnt(0)
	v_mfma_f32_16x16x32_bf16 v[126:129], v[134:137], v[166:169], v[126:129]
	v_mfma_f32_16x16x32_bf16 v[122:125], v[142:145], v[166:169], v[122:125]
	v_mfma_f32_16x16x32_bf16 v[110:113], v[134:137], v[174:177], v[110:113]
	v_mfma_f32_16x16x32_bf16 v[106:109], v[142:145], v[174:177], v[106:109]
	v_mfma_f32_16x16x32_bf16 v[98:101], v[134:137], v[182:185], v[98:101]
	v_mfma_f32_16x16x32_bf16 v[90:93], v[142:145], v[182:185], v[90:93]
	v_mfma_f32_16x16x32_bf16 v[82:85], v[134:137], v[190:193], v[82:85]
	v_mfma_f32_16x16x32_bf16 v[74:77], v[142:145], v[190:193], v[74:77]
	s_setprio 0
	s_setprio 1
	v_mfma_f32_16x16x32_bf16 v[126:129], v[138:141], v[170:173], v[126:129]
	v_mfma_f32_16x16x32_bf16 v[122:125], v[146:149], v[170:173], v[122:125]
	v_mfma_f32_16x16x32_bf16 v[110:113], v[138:141], v[178:181], v[110:113]
	v_mfma_f32_16x16x32_bf16 v[106:109], v[146:149], v[178:181], v[106:109]
	v_mfma_f32_16x16x32_bf16 v[98:101], v[138:141], v[186:189], v[98:101]
	v_mfma_f32_16x16x32_bf16 v[90:93], v[146:149], v[186:189], v[90:93]
	v_mfma_f32_16x16x32_bf16 v[82:85], v[138:141], v[210:213], v[82:85]
	v_mfma_f32_16x16x32_bf16 v[74:77], v[146:149], v[210:213], v[74:77]
	s_setprio 0
	s_setprio 1
	v_mfma_f32_16x16x32_bf16 v[118:121], v[150:153], v[166:169], v[118:121]
	v_mfma_f32_16x16x32_bf16 v[114:117], v[158:161], v[166:169], v[114:117]
	v_mfma_f32_16x16x32_bf16 v[102:105], v[150:153], v[174:177], v[102:105]
	v_mfma_f32_16x16x32_bf16 v[94:97], v[158:161], v[174:177], v[94:97]
	v_mfma_f32_16x16x32_bf16 v[86:89], v[150:153], v[182:185], v[86:89]
	v_mfma_f32_16x16x32_bf16 v[78:81], v[158:161], v[182:185], v[78:81]
	v_mfma_f32_16x16x32_bf16 v[70:73], v[150:153], v[190:193], v[70:73]
	v_mfma_f32_16x16x32_bf16 v[66:69], v[158:161], v[190:193], v[66:69]
	s_setprio 0
	s_setprio 1
	v_mfma_f32_16x16x32_bf16 v[118:121], v[154:157], v[170:173], v[118:121]
	v_mfma_f32_16x16x32_bf16 v[114:117], v[162:165], v[170:173], v[114:117]
	v_mfma_f32_16x16x32_bf16 v[102:105], v[154:157], v[178:181], v[102:105]
	v_mfma_f32_16x16x32_bf16 v[94:97], v[162:165], v[178:181], v[94:97]
	v_mfma_f32_16x16x32_bf16 v[86:89], v[154:157], v[186:189], v[86:89]
	v_mfma_f32_16x16x32_bf16 v[78:81], v[162:165], v[186:189], v[78:81]
	v_mfma_f32_16x16x32_bf16 v[70:73], v[154:157], v[210:213], v[70:73]
	v_mfma_f32_16x16x32_bf16 v[66:69], v[162:165], v[210:213], v[66:69]
	s_setprio 0
	s_barrier
; #define PG8_LDA(dst, b, h) do { _Pragma("unroll") for (int m = 0; m < 4; ++m) _Pragma("unroll") for (int k = 0; k < 2; ++k) dst[m][k] = *(const LAS bf16x8*)(lds + PG8_SA(b, h) + aoff + m * 2048 + k * 1024); } while (0)
; #define PG8_MMA(ai, bj, At, Bt) do { __builtin_amdgcn_s_setprio(1); _Pragma("unroll") for (int m = 0; m < 4; ++m) _Pragma("unroll") for (int n = 0; n < 2; ++n) _Pragma("unroll") for (int k = 0; k < 2; ++k) \
;         acc[ai][bj][m][n] = __builtin_amdgcn_mfma_f32_16x16x32_bf16(Bt[n][k], At[m][k], acc[ai][bj][m][n], 0, 0, 0); __builtin_amdgcn_s_setprio(0); } while (0)
; #define PG8_WAIT_V(n) asm volatile("s_waitcnt vmcnt(" #n ")" ::: "memory")
; #define PG8_WAIT_L(n) asm volatile("s_waitcnt lgkmcnt(" #n ")" ::: "memory")
; #define PG8_BAR __builtin_amdgcn_s_barrier()
; #define PG8_SCHED __builtin_amdgcn_sched_barrier(0)
; #define PG8_STA(bufoff, gbase, ld) PG8_STAGE(bufoff, gbase, RA0 * (unsigned)(ld) + CC0, RA1 * (unsigned)(ld) + CC1)
; #define PG8_STB(bufoff, gbase, ld) PG8_STAGE(bufoff, gbase, RB0 * (unsigned)(ld) + CC0, RB1 * (unsigned)(ld) + CC1)
; __device__ __forceinline__ void gemm_phase(LAS unsigned char* lds, const Sched& S, const Epi& E) {
;     ...
;             PG8_LDA(At, 1, 1); PG8_STB(PG8_SB(1, 0), b3, xldb); PG8_STB(PG8_SB(1, 1), b3 + xhB, xldb); PG8_STA(PG8_SA(1, 0), a3, xlda);
;             PG8_WAIT_V(8); PG8_WAIT_L(0); PG8_BAR; PG8_MMA(1, 0, At, B0); PG8_MMA(1, 1, At, B1); PG8_BAR; PG8_SCHED;
;         }
	s_add_i32 s8, s28, s25
	v_lshl_add_u64 v[218:219], v[222:223], 0, s[52:53]
	s_mov_b32 m0, s8
	ds_read_b128 v[166:169], v0 offset:49152
	ds_read_b128 v[170:173], v0 offset:50176
	ds_read_b128 v[174:177], v0 offset:51200
	ds_read_b128 v[178:181], v0 offset:52224
	ds_read_b128 v[182:185], v0 offset:53248
	ds_read_b128 v[186:189], v0 offset:54272
	ds_read_b128 v[190:193], v0 offset:55296
	ds_read_b128 v[210:213], v0 offset:56320
	global_load_lds_dwordx4 v[218:219], off
	v_lshl_add_u64 v[218:219], v[224:225], 0, s[52:53]
	s_add_i32 m0, s8, 0x2000
	s_add_i32 s8, s29, s25
	global_load_lds_dwordx4 v[218:219], off
	v_lshl_add_u64 v[214:215], v[214:215], 0, s[52:53]
	s_mov_b32 m0, s8
	s_nop 0
	global_load_lds_dwordx4 v[214:215], off
	v_lshl_add_u64 v[214:215], v[216:217], 0, s[52:53]
	s_add_i32 m0, s8, 0x2000
	s_nop 0
	global_load_lds_dwordx4 v[214:215], off
	v_lshl_add_u64 v[214:215], v[226:227], 0, s[52:53]
	s_mov_b32 m0, s90
	s_nop 0
	global_load_lds_dwordx4 v[214:215], off
	v_lshl_add_u64 v[214:215], v[228:229], 0, s[52:53]
	s_mov_b32 m0, s73
	s_nop 0
	global_load_lds_dwordx4 v[214:215], off
	s_nop 0
	s_waitcnt vmcnt(8)
	s_waitcnt lgkmcnt(0)
	s_barrier
	s_setprio 1
	s_waitcnt lgkmcnt(0)
	v_mfma_f32_16x16x32_bf16 v[62:65], v[134:137], v[166:169], v[62:65]
	v_mfma_f32_16x16x32_bf16 v[58:61], v[142:145], v[166:169], v[58:61]
	v_mfma_f32_16x16x32_bf16 v[46:49], v[134:137], v[174:177], v[46:49]
	v_mfma_f32_16x16x32_bf16 v[42:45], v[142:145], v[174:177], v[42:45]
	v_mfma_f32_16x16x32_bf16 v[30:33], v[134:137], v[182:185], v[30:33]
	v_mfma_f32_16x16x32_bf16 v[26:29], v[142:145], v[182:185], v[26:29]
	v_mfma_f32_16x16x32_bf16 v[14:17], v[134:137], v[190:193], v[14:17]
	v_mfma_f32_16x16x32_bf16 v[10:13], v[142:145], v[190:193], v[10:13]
	s_setprio 0
	s_setprio 1
	v_mfma_f32_16x16x32_bf16 v[62:65], v[138:141], v[170:173], v[62:65]
	v_mfma_f32_16x16x32_bf16 v[58:61], v[146:149], v[170:173], v[58:61]
	v_mfma_f32_16x16x32_bf16 v[46:49], v[138:141], v[178:181], v[46:49]
	v_mfma_f32_16x16x32_bf16 v[42:45], v[146:149], v[178:181], v[42:45]
	v_mfma_f32_16x16x32_bf16 v[30:33], v[138:141], v[186:189], v[30:33]
	v_mfma_f32_16x16x32_bf16 v[26:29], v[146:149], v[186:189], v[26:29]
	v_mfma_f32_16x16x32_bf16 v[14:17], v[138:141], v[210:213], v[14:17]
	v_mfma_f32_16x16x32_bf16 v[10:13], v[146:149], v[210:213], v[10:13]
	s_setprio 0
	s_setprio 1
	v_mfma_f32_16x16x32_bf16 v[54:57], v[150:153], v[166:169], v[54:57]
	v_mfma_f32_16x16x32_bf16 v[50:53], v[158:161], v[166:169], v[50:53]
	v_mfma_f32_16x16x32_bf16 v[38:41], v[150:153], v[174:177], v[38:41]
	v_mfma_f32_16x16x32_bf16 v[34:37], v[158:161], v[174:177], v[34:37]
	v_mfma_f32_16x16x32_bf16 v[22:25], v[150:153], v[182:185], v[22:25]
	v_mfma_f32_16x16x32_bf16 v[18:21], v[158:161], v[182:185], v[18:21]
	v_mfma_f32_16x16x32_bf16 v[6:9], v[150:153], v[190:193], v[6:9]
	v_mfma_f32_16x16x32_bf16 v[2:5], v[158:161], v[190:193], v[2:5]
	s_setprio 0
	s_setprio 1
	v_mfma_f32_16x16x32_bf16 v[54:57], v[154:157], v[170:173], v[54:57]
	v_mfma_f32_16x16x32_bf16 v[50:53], v[162:165], v[170:173], v[50:53]
	v_mfma_f32_16x16x32_bf16 v[38:41], v[154:157], v[178:181], v[38:41]
	v_mfma_f32_16x16x32_bf16 v[34:37], v[162:165], v[178:181], v[34:37]
	v_mfma_f32_16x16x32_bf16 v[22:25], v[154:157], v[186:189], v[22:25]
	v_mfma_f32_16x16x32_bf16 v[18:21], v[162:165], v[186:189], v[18:21]
	v_mfma_f32_16x16x32_bf16 v[6:9], v[154:157], v[210:213], v[6:9]
	v_mfma_f32_16x16x32_bf16 v[2:5], v[162:165], v[210:213], v[2:5]
	s_setprio 0
	s_barrier
	s_add_u32 vcc_lo, vcc_lo, 0x100
	s_addc_u32 vcc_hi, vcc_hi, 0
	s_add_u32 s2, s2, 0x100
	s_addc_u32 s72, s72, 0
	s_cmp_ge_i32 s24, s68
	s_mov_b32 s8, s24
	s_cbranch_scc0 .LBB0_263
	s_nop 0
	s_mov_b32 s92, s3
	s_movk_i32 s93, 0x3fff
	s_movk_i32 s3, 0x2000
	s_and_b64 vcc, exec, s[44:45]
	s_cbranch_vccz .LBB0_266
